# v52 + P4: early wave half takes its alignment barrier after its SwiGLU epilogue (epilogue overlaps the late half's last MFMA segment)
# baseline (speedup 1.0000x reference)
; __host__ __device__ __forceinline__ size_t tl_off(int row, int k, int K) { return ((((size_t)(row >> 4) * (size_t)(K >> 5)) + (size_t)(k >> 5)) << 9) + (size_t)((row & 15) * 32 + (k & 31)); }
; __device__ __forceinline__ unsigned cvt_pk_bf16(float lo, float hi) { unsigned r; asm volatile("v_cvt_pk_bf16_f32 %0, %1, %2" : "=v"(r) : "v"(lo), "v"(hi)); return r; }
; #define PG8_BAR __builtin_amdgcn_s_barrier()
;     __device__ __forceinline__ void operator()(const f32x4 (&acc)[2][2][4][2], const Unit& u, int wr, int wc, int fr, int fq) const {
;         const int row0 = u.pm * BM + wr * 64 + fr, col0 = u.pn * HALF + wc * 32 + 8 * fq;
;         float sv[8];
; #pragma unroll
;         for (int i = 0; i < 8; ++i) sv[i] = ssl[wr * 64 + fr + (i >> 2) * HALF + (i & 3) * 16];
;         asm volatile("" ::: "memory");
; #pragma unroll
;         for (int i = 0; i < 8; ++i) { const int ai = i >> 2, m = i & 3;
;             const float rstd = __builtin_amdgcn_rsqf(sv[i] * (1.0f / (float)D) + EPS), ne = -LOG2E * rstd, r2 = rstd * rstd;
;             unsigned w[4];
; #pragma unroll
;             for (int n = 0; n < 2; ++n)
; #pragma unroll
;                 for (int h = 0; h < 2; ++h) {
;                     const f32x2 g = {acc[ai][0][m][n][2 * h], acc[ai][0][m][n][2 * h + 1]}, up = {acc[ai][1][m][n][2 * h], acc[ai][1][m][n][2 * h + 1]};
;                     const f32x2 t = g * ne; f32x2 e; e.x = __builtin_amdgcn_exp2f(t.x); e.y = __builtin_amdgcn_exp2f(t.y);
;                     const f32x2 d = e + 1.0f; f32x2 r; r.x = __builtin_amdgcn_rcpf(d.x); r.y = __builtin_amdgcn_rcpf(d.y);
;                     const f32x2 a = (g * up) * (r * r2);
;                     w[2 * n + h] = cvt_pk_bf16(a.x, a.y); }
;             __builtin_nontemporal_store((u32x4){w[0], w[1], w[2], w[3]}, (u32x4*)(ACT + tl_off(row0 + ai * HALF + m * 16, col0, FF)));
;         }
;     ...
;         if constexpr (ALIGN_EPI) { if (wr == 0) PG8_BAR; }
.LBB0_489:
.LBB0_491:
	v_mov_b32_e32 v128, v148
	v_mov_b32_e32 v136, v149
	s_add_i32 s1, s22, s62
	v_lshlrev_b32_e32 v157, 3, v136
	v_lshl_add_u32 v136, v128, 2, s74
	ds_read2_b32 v[158:159], v136 offset1:16
	ds_read2_b32 v[142:143], v136 offset0:32 offset1:48
	ds_read2_b32 v[140:141], v136 offset0:128 offset1:144
	ds_read2_b32 v[138:139], v136 offset0:160 offset1:176
	v_add_u32_e32 v156, s1, v128
	s_waitcnt lgkmcnt(3)
	v_fmamk_f32 v137, v158, 0x3a800000, v155
	v_rsq_f32_e32 v158, v137
	v_lshlrev_b32_e32 v162, 5, v128
	v_pk_mul_f32 v[126:127], v[122:123], v[126:127]
	v_mul_f32_e32 v128, 0xbfb8aa3b, v158
	v_pk_mul_f32 v[160:161], v[120:121], v[128:129] op_sel_hi:[1,0]
	v_pk_mul_f32 v[122:123], v[122:123], v[128:129] op_sel_hi:[1,0]
	v_exp_f32_e32 v160, v160
	v_exp_f32_e32 v161, v161
	v_exp_f32_e32 v122, v122
	v_exp_f32_e32 v123, v123
	v_mul_f32_e32 v158, v158, v158
	v_pk_add_f32 v[160:161], v[160:161], 1.0 op_sel_hi:[1,0]
	v_pk_mul_f32 v[120:121], v[120:121], v[124:125]
	v_rcp_f32_e32 v160, v160
	v_rcp_f32_e32 v161, v161
	v_pk_add_f32 v[122:123], v[122:123], 1.0 op_sel_hi:[1,0]
	s_lshl_b32 s0, s0, 7
	v_rcp_f32_e32 v122, v122
	v_pk_mul_f32 v[124:125], v[158:159], v[160:161] op_sel_hi:[0,1]
	v_rcp_f32_e32 v123, v123
	v_pk_mul_f32 v[120:121], v[120:121], v[124:125]
	v_pk_mul_f32 v[124:125], v[112:113], v[128:129] op_sel_hi:[1,0]
	v_cvt_pk_bf16_f32 v120, v120, v121
	v_pk_mul_f32 v[122:123], v[158:159], v[122:123] op_sel_hi:[0,1]
	v_exp_f32_e32 v124, v124
	v_exp_f32_e32 v125, v125
	v_pk_mul_f32 v[122:123], v[126:127], v[122:123]
	v_pk_mul_f32 v[112:113], v[112:113], v[116:117]
	v_cvt_pk_bf16_f32 v121, v122, v123
	v_pk_add_f32 v[122:123], v[124:125], 1.0 op_sel_hi:[1,0]
	v_pk_mul_f32 v[124:125], v[114:115], v[128:129] op_sel_hi:[1,0]
	v_rcp_f32_e32 v122, v122
	v_exp_f32_e32 v124, v124
	v_exp_f32_e32 v125, v125
	v_rcp_f32_e32 v123, v123
	v_pk_mul_f32 v[114:115], v[114:115], v[118:119]
	s_or_b32 s0, s0, s63
	v_pk_add_f32 v[116:117], v[124:125], 1.0 op_sel_hi:[1,0]
	v_pk_mul_f32 v[118:119], v[158:159], v[122:123] op_sel_hi:[0,1]
	v_rcp_f32_e32 v116, v116
	v_rcp_f32_e32 v117, v117
	v_pk_mul_f32 v[112:113], v[112:113], v[118:119]
	v_add_u32_e32 v136, s0, v157
	v_cvt_pk_bf16_f32 v122, v112, v113
	v_pk_mul_f32 v[112:113], v[158:159], v[116:117] op_sel_hi:[0,1]
	v_pk_mul_f32 v[112:113], v[114:115], v[112:113]
	v_fmamk_f32 v114, v159, 0x3a800000, v155
	v_rsq_f32_e32 v115, v114
	v_ashrrev_i32_e32 v136, 5, v136
	v_ashrrev_i32_e32 v137, 31, v136
	v_cvt_pk_bf16_f32 v123, v112, v113
	v_mul_f32_e32 v114, 0xbfb8aa3b, v115
	v_pk_mul_f32 v[116:117], v[104:105], v[114:115] op_sel_hi:[1,0]
	v_ashrrev_i32_e32 v112, 4, v156
	v_exp_f32_e32 v116, v116
	v_exp_f32_e32 v117, v117
	v_pk_mul_f32 v[110:111], v[106:107], v[110:111]
	v_pk_mul_f32 v[106:107], v[106:107], v[114:115] op_sel_hi:[1,0]
	v_and_b32_e32 v162, 0x1e0, v162
	v_mad_i64_i32 v[112:113], s[0:1], v112, s75, v[136:137]
	v_pk_add_f32 v[116:117], v[116:117], 1.0 op_sel_hi:[1,0]
	v_exp_f32_e32 v106, v106
	v_exp_f32_e32 v107, v107
	v_and_or_b32 v157, v157, 24, v162
	v_lshlrev_b64 v[112:113], 10, v[112:113]
	v_rcp_f32_e32 v116, v116
	v_rcp_f32_e32 v117, v117
	v_lshl_add_u64 v[112:113], s[24:25], 0, v[112:113]
	v_lshlrev_b32_e32 v128, 1, v157
	v_lshl_add_u64 v[112:113], v[112:113], 0, v[128:129]
	global_store_dwordx4 v[112:113], v[120:123], off nt
	v_mul_f32_e32 v112, v115, v115
	v_pk_add_f32 v[106:107], v[106:107], 1.0 op_sel_hi:[1,0]
	v_pk_mul_f32 v[104:105], v[104:105], v[108:109]
	v_pk_mul_f32 v[108:109], v[112:113], v[116:117] op_sel_hi:[0,1]
	v_rcp_f32_e32 v106, v106
	v_rcp_f32_e32 v107, v107
	v_pk_mul_f32 v[104:105], v[104:105], v[108:109]
	v_pk_mul_f32 v[108:109], v[96:97], v[114:115] op_sel_hi:[1,0]
	v_cvt_pk_bf16_f32 v104, v104, v105
	v_pk_mul_f32 v[106:107], v[112:113], v[106:107] op_sel_hi:[0,1]
	v_exp_f32_e32 v108, v108
	v_exp_f32_e32 v109, v109
	v_pk_mul_f32 v[106:107], v[110:111], v[106:107]
	v_pk_mul_f32 v[96:97], v[96:97], v[100:101]
	v_cvt_pk_bf16_f32 v105, v106, v107
	v_pk_add_f32 v[106:107], v[108:109], 1.0 op_sel_hi:[1,0]
	v_pk_mul_f32 v[108:109], v[98:99], v[114:115] op_sel_hi:[1,0]
	v_rcp_f32_e32 v106, v106
	v_exp_f32_e32 v108, v108
	v_exp_f32_e32 v109, v109
	v_rcp_f32_e32 v107, v107
	v_pk_mul_f32 v[98:99], v[98:99], v[102:103]
	v_pk_mul_f32 v[94:95], v[90:91], v[94:95]
	v_pk_add_f32 v[100:101], v[108:109], 1.0 op_sel_hi:[1,0]
	v_pk_mul_f32 v[102:103], v[112:113], v[106:107] op_sel_hi:[0,1]
	v_rcp_f32_e32 v100, v100
	v_rcp_f32_e32 v101, v101
	v_pk_mul_f32 v[96:97], v[96:97], v[102:103]
	v_pk_mul_f32 v[78:79], v[74:75], v[78:79]
	v_cvt_pk_bf16_f32 v106, v96, v97
	v_pk_mul_f32 v[96:97], v[112:113], v[100:101] op_sel_hi:[0,1]
	v_pk_mul_f32 v[96:97], v[98:99], v[96:97]
	v_pk_mul_f32 v[46:47], v[42:43], v[46:47]
	v_cvt_pk_bf16_f32 v107, v96, v97
	s_waitcnt lgkmcnt(2)
; __host__ __device__ __forceinline__ size_t tl_off(int row, int k, int K) { return ((((size_t)(row >> 4) * (size_t)(K >> 5)) + (size_t)(k >> 5)) << 9) + (size_t)((row & 15) * 32 + (k & 31)); }
; __device__ __forceinline__ unsigned cvt_pk_bf16(float lo, float hi) { unsigned r; asm volatile("v_cvt_pk_bf16_f32 %0, %1, %2" : "=v"(r) : "v"(lo), "v"(hi)); return r; }
;     __device__ __forceinline__ void operator()(const f32x4 (&acc)[2][2][4][2], const Unit& u, int wr, int wc, int fr, int fq) const {
;     ...
;         for (int i = 0; i < 8; ++i) { const int ai = i >> 2, m = i & 3;
;             const float rstd = __builtin_amdgcn_rsqf(sv[i] * (1.0f / (float)D) + EPS), ne = -LOG2E * rstd, r2 = rstd * rstd;
;             unsigned w[4];
; #pragma unroll
;             for (int n = 0; n < 2; ++n)
; #pragma unroll
;                 for (int h = 0; h < 2; ++h) {
;                     const f32x2 g = {acc[ai][0][m][n][2 * h], acc[ai][0][m][n][2 * h + 1]}, up = {acc[ai][1][m][n][2 * h], acc[ai][1][m][n][2 * h + 1]};
;                     const f32x2 t = g * ne; f32x2 e; e.x = __builtin_amdgcn_exp2f(t.x); e.y = __builtin_amdgcn_exp2f(t.y);
;                     const f32x2 d = e + 1.0f; f32x2 r; r.x = __builtin_amdgcn_rcpf(d.x); r.y = __builtin_amdgcn_rcpf(d.y);
;                     const f32x2 a = (g * up) * (r * r2);
;                     w[2 * n + h] = cvt_pk_bf16(a.x, a.y); }
;             __builtin_nontemporal_store((u32x4){w[0], w[1], w[2], w[3]}, (u32x4*)(ACT + tl_off(row0 + ai * HALF + m * 16, col0, FF)));
	v_fmamk_f32 v97, v142, 0x3a800000, v155
	v_rsq_f32_e32 v99, v97
	v_add_u32_e32 v96, 16, v156
	v_ashrrev_i32_e32 v96, 4, v96
	v_mad_i64_i32 v[96:97], s[0:1], v96, s75, v[136:137]
	v_mul_f32_e32 v98, 0xbfb8aa3b, v99
	v_pk_mul_f32 v[100:101], v[88:89], v[98:99] op_sel_hi:[1,0]
	v_pk_mul_f32 v[90:91], v[90:91], v[98:99] op_sel_hi:[1,0]
	v_exp_f32_e32 v100, v100
	v_exp_f32_e32 v101, v101
	v_exp_f32_e32 v90, v90
	v_exp_f32_e32 v91, v91
	v_lshlrev_b64 v[96:97], 10, v[96:97]
	v_pk_add_f32 v[100:101], v[100:101], 1.0 op_sel_hi:[1,0]
	v_lshl_add_u64 v[96:97], s[24:25], 0, v[96:97]
	v_rcp_f32_e32 v100, v100
	v_rcp_f32_e32 v101, v101
	v_lshl_add_u64 v[96:97], v[96:97], 0, v[128:129]
	global_store_dwordx4 v[96:97], v[104:107], off nt
	v_mul_f32_e32 v96, v99, v99
	v_pk_add_f32 v[90:91], v[90:91], 1.0 op_sel_hi:[1,0]
	v_pk_mul_f32 v[88:89], v[88:89], v[92:93]
	v_pk_mul_f32 v[92:93], v[96:97], v[100:101] op_sel_hi:[0,1]
	v_rcp_f32_e32 v90, v90
	v_rcp_f32_e32 v91, v91
	v_pk_mul_f32 v[88:89], v[88:89], v[92:93]
	v_pk_mul_f32 v[92:93], v[80:81], v[98:99] op_sel_hi:[1,0]
	v_cvt_pk_bf16_f32 v88, v88, v89
	v_pk_mul_f32 v[90:91], v[96:97], v[90:91] op_sel_hi:[0,1]
	v_exp_f32_e32 v92, v92
	v_exp_f32_e32 v93, v93
	v_pk_mul_f32 v[90:91], v[94:95], v[90:91]
	v_pk_mul_f32 v[80:81], v[80:81], v[84:85]
	v_cvt_pk_bf16_f32 v89, v90, v91
	v_pk_add_f32 v[90:91], v[92:93], 1.0 op_sel_hi:[1,0]
	v_pk_mul_f32 v[92:93], v[82:83], v[98:99] op_sel_hi:[1,0]
	v_rcp_f32_e32 v90, v90
	v_exp_f32_e32 v92, v92
	v_exp_f32_e32 v93, v93
	v_rcp_f32_e32 v91, v91
	v_pk_mul_f32 v[82:83], v[82:83], v[86:87]
	v_pk_mul_f32 v[30:31], v[26:27], v[30:31]
	v_pk_add_f32 v[84:85], v[92:93], 1.0 op_sel_hi:[1,0]
	v_pk_mul_f32 v[86:87], v[96:97], v[90:91] op_sel_hi:[0,1]
	v_rcp_f32_e32 v84, v84
	v_rcp_f32_e32 v85, v85
	v_pk_mul_f32 v[80:81], v[80:81], v[86:87]
	v_pk_mul_f32 v[14:15], v[10:11], v[14:15]
	v_cvt_pk_bf16_f32 v90, v80, v81
	v_pk_mul_f32 v[80:81], v[96:97], v[84:85] op_sel_hi:[0,1]
	v_pk_mul_f32 v[80:81], v[82:83], v[80:81]
	s_andn2_b64 vcc, exec, s[4:5]
	v_cvt_pk_bf16_f32 v91, v80, v81
	v_fmamk_f32 v81, v143, 0x3a800000, v155
	v_rsq_f32_e32 v83, v81
	v_add_u32_e32 v80, 32, v156
	v_ashrrev_i32_e32 v80, 4, v80
	v_mad_i64_i32 v[80:81], s[0:1], v80, s75, v[136:137]
	v_mul_f32_e32 v82, 0xbfb8aa3b, v83
	v_pk_mul_f32 v[84:85], v[72:73], v[82:83] op_sel_hi:[1,0]
	v_pk_mul_f32 v[74:75], v[74:75], v[82:83] op_sel_hi:[1,0]
	v_exp_f32_e32 v84, v84
	v_exp_f32_e32 v85, v85
	v_exp_f32_e32 v74, v74
	v_exp_f32_e32 v75, v75
	v_lshlrev_b64 v[80:81], 10, v[80:81]
	v_pk_add_f32 v[84:85], v[84:85], 1.0 op_sel_hi:[1,0]
	v_lshl_add_u64 v[80:81], s[24:25], 0, v[80:81]
	v_rcp_f32_e32 v84, v84
	v_rcp_f32_e32 v85, v85
	v_lshl_add_u64 v[80:81], v[80:81], 0, v[128:129]
	global_store_dwordx4 v[80:81], v[88:91], off nt
	v_mul_f32_e32 v80, v83, v83
	v_pk_add_f32 v[74:75], v[74:75], 1.0 op_sel_hi:[1,0]
	v_pk_mul_f32 v[72:73], v[72:73], v[76:77]
	v_pk_mul_f32 v[76:77], v[80:81], v[84:85] op_sel_hi:[0,1]
	v_rcp_f32_e32 v74, v74
	v_rcp_f32_e32 v75, v75
	v_pk_mul_f32 v[72:73], v[72:73], v[76:77]
	v_pk_mul_f32 v[76:77], v[60:61], v[82:83] op_sel_hi:[1,0]
	v_cvt_pk_bf16_f32 v72, v72, v73
	v_pk_mul_f32 v[74:75], v[80:81], v[74:75] op_sel_hi:[0,1]
	v_exp_f32_e32 v76, v76
	v_exp_f32_e32 v77, v77
	v_pk_mul_f32 v[74:75], v[78:79], v[74:75]
	v_pk_mul_f32 v[60:61], v[60:61], v[64:65]
	v_cvt_pk_bf16_f32 v73, v74, v75
	v_pk_add_f32 v[74:75], v[76:77], 1.0 op_sel_hi:[1,0]
	v_pk_mul_f32 v[76:77], v[62:63], v[82:83] op_sel_hi:[1,0]
	v_rcp_f32_e32 v74, v74
	v_exp_f32_e32 v76, v76
	v_exp_f32_e32 v77, v77
	v_rcp_f32_e32 v75, v75
	v_pk_mul_f32 v[62:63], v[62:63], v[66:67]
	s_mov_b64 s[4:5], -1
	v_pk_add_f32 v[64:65], v[76:77], 1.0 op_sel_hi:[1,0]
	v_pk_mul_f32 v[66:67], v[80:81], v[74:75] op_sel_hi:[0,1]
	v_rcp_f32_e32 v64, v64
	v_rcp_f32_e32 v65, v65
	v_pk_mul_f32 v[60:61], v[60:61], v[66:67]
	v_pk_mul_f32 v[66:67], v[58:59], v[70:71]
	v_cvt_pk_bf16_f32 v74, v60, v61
	v_pk_mul_f32 v[60:61], v[80:81], v[64:65] op_sel_hi:[0,1]
	v_pk_mul_f32 v[60:61], v[62:63], v[60:61]
	s_nop 0
	v_cvt_pk_bf16_f32 v75, v60, v61
	s_waitcnt lgkmcnt(1)
	v_fmamk_f32 v61, v140, 0x3a800000, v155
	v_rsq_f32_e32 v63, v61
	v_add_u32_e32 v60, 48, v156
	v_ashrrev_i32_e32 v60, 4, v60
	v_mad_i64_i32 v[60:61], s[0:1], v60, s75, v[136:137]
	v_mul_f32_e32 v62, 0xbfb8aa3b, v63
	v_pk_mul_f32 v[64:65], v[56:57], v[62:63] op_sel_hi:[1,0]
	v_pk_mul_f32 v[58:59], v[58:59], v[62:63] op_sel_hi:[1,0]
	v_exp_f32_e32 v64, v64
	v_exp_f32_e32 v65, v65
	v_exp_f32_e32 v58, v58
	v_exp_f32_e32 v59, v59
	v_lshlrev_b64 v[60:61], 10, v[60:61]
	v_pk_add_f32 v[64:65], v[64:65], 1.0 op_sel_hi:[1,0]
	v_lshl_add_u64 v[60:61], s[24:25], 0, v[60:61]
	v_rcp_f32_e32 v64, v64
	v_rcp_f32_e32 v65, v65
	v_lshl_add_u64 v[60:61], v[60:61], 0, v[128:129]
	global_store_dwordx4 v[60:61], v[72:75], off nt
	v_mul_f32_e32 v60, v63, v63
	v_pk_add_f32 v[58:59], v[58:59], 1.0 op_sel_hi:[1,0]
	v_pk_mul_f32 v[56:57], v[56:57], v[68:69]
	v_pk_mul_f32 v[64:65], v[60:61], v[64:65] op_sel_hi:[0,1]
	v_rcp_f32_e32 v58, v58
	v_rcp_f32_e32 v59, v59
	v_pk_mul_f32 v[56:57], v[56:57], v[64:65]
	v_pk_mul_f32 v[64:65], v[48:49], v[62:63] op_sel_hi:[1,0]
	v_pk_mul_f32 v[62:63], v[50:51], v[62:63] op_sel_hi:[1,0]
	v_exp_f32_e32 v64, v64
	v_exp_f32_e32 v65, v65
	v_pk_mul_f32 v[58:59], v[60:61], v[58:59] op_sel_hi:[0,1]
	v_exp_f32_e32 v62, v62
	v_exp_f32_e32 v63, v63
	v_pk_mul_f32 v[58:59], v[66:67], v[58:59]
	v_cvt_pk_bf16_f32 v56, v56, v57
	v_pk_mul_f32 v[48:49], v[48:49], v[52:53]
	v_cvt_pk_bf16_f32 v57, v58, v59
	v_pk_add_f32 v[58:59], v[64:65], 1.0 op_sel_hi:[1,0]
	v_pk_add_f32 v[52:53], v[62:63], 1.0 op_sel_hi:[1,0]
	v_rcp_f32_e32 v58, v58
; __host__ __device__ __forceinline__ size_t tl_off(int row, int k, int K) { return ((((size_t)(row >> 4) * (size_t)(K >> 5)) + (size_t)(k >> 5)) << 9) + (size_t)((row & 15) * 32 + (k & 31)); }
; __device__ __forceinline__ unsigned cvt_pk_bf16(float lo, float hi) { unsigned r; asm volatile("v_cvt_pk_bf16_f32 %0, %1, %2" : "=v"(r) : "v"(lo), "v"(hi)); return r; }
; #define PG8_BAR __builtin_amdgcn_s_barrier()
;     __device__ __forceinline__ void operator()(const f32x4 (&acc)[2][2][4][2], const Unit& u, int wr, int wc, int fr, int fq) const {
;     ...
;                     const f32x2 g = {acc[ai][0][m][n][2 * h], acc[ai][0][m][n][2 * h + 1]}, up = {acc[ai][1][m][n][2 * h], acc[ai][1][m][n][2 * h + 1]};
;                     const f32x2 t = g * ne; f32x2 e; e.x = __builtin_amdgcn_exp2f(t.x); e.y = __builtin_amdgcn_exp2f(t.y);
;                     const f32x2 d = e + 1.0f; f32x2 r; r.x = __builtin_amdgcn_rcpf(d.x); r.y = __builtin_amdgcn_rcpf(d.y);
;                     const f32x2 a = (g * up) * (r * r2);
;                     w[2 * n + h] = cvt_pk_bf16(a.x, a.y); }
;             __builtin_nontemporal_store((u32x4){w[0], w[1], w[2], w[3]}, (u32x4*)(ACT + tl_off(row0 + ai * HALF + m * 16, col0, FF)));
;         }
;     ...
;         if constexpr (ALIGN_EPI) { if (wr == 0) PG8_BAR; }
;         if constexpr (!Epi::AFTER_DRAIN) { int fr_ = fr, fq_ = fq; asm volatile("" : "+v"(fr_), "+v"(fq_));
;             E(acc, cur, wr, wc, fr_, fq_); S.done(cur); }
;         if (!has_next) break;
;         cur = nxt; cA = nA; cB = nB; ++ui;
;         if constexpr (ALIGN_EPI) { if (wr == 1) PG8_BAR; }
	v_rcp_f32_e32 v59, v59
	v_rcp_f32_e32 v52, v52
	v_rcp_f32_e32 v53, v53
	v_pk_mul_f32 v[50:51], v[50:51], v[54:55]
	v_pk_mul_f32 v[54:55], v[60:61], v[58:59] op_sel_hi:[0,1]
	v_pk_mul_f32 v[48:49], v[48:49], v[54:55]
	s_nop 0
	v_cvt_pk_bf16_f32 v58, v48, v49
	v_pk_mul_f32 v[48:49], v[60:61], v[52:53] op_sel_hi:[0,1]
	v_pk_mul_f32 v[48:49], v[50:51], v[48:49]
	s_nop 0
	v_cvt_pk_bf16_f32 v59, v48, v49
	v_fmamk_f32 v49, v141, 0x3a800000, v155
	v_rsq_f32_e32 v51, v49
	v_add_u32_e32 v48, 0x80, v156
	v_ashrrev_i32_e32 v48, 4, v48
	v_mad_i64_i32 v[48:49], s[0:1], v48, s75, v[136:137]
	v_mul_f32_e32 v50, 0xbfb8aa3b, v51
	v_pk_mul_f32 v[52:53], v[40:41], v[50:51] op_sel_hi:[1,0]
	v_pk_mul_f32 v[42:43], v[42:43], v[50:51] op_sel_hi:[1,0]
	v_exp_f32_e32 v52, v52
	v_exp_f32_e32 v53, v53
	v_exp_f32_e32 v42, v42
	v_exp_f32_e32 v43, v43
	v_lshlrev_b64 v[48:49], 10, v[48:49]
	v_pk_add_f32 v[52:53], v[52:53], 1.0 op_sel_hi:[1,0]
	v_lshl_add_u64 v[48:49], s[24:25], 0, v[48:49]
	v_rcp_f32_e32 v52, v52
	v_rcp_f32_e32 v53, v53
	v_lshl_add_u64 v[48:49], v[48:49], 0, v[128:129]
	global_store_dwordx4 v[48:49], v[56:59], off nt
	v_mul_f32_e32 v48, v51, v51
	v_pk_add_f32 v[42:43], v[42:43], 1.0 op_sel_hi:[1,0]
	v_pk_mul_f32 v[40:41], v[40:41], v[44:45]
	v_pk_mul_f32 v[44:45], v[48:49], v[52:53] op_sel_hi:[0,1]
	v_rcp_f32_e32 v42, v42
	v_rcp_f32_e32 v43, v43
	v_pk_mul_f32 v[40:41], v[40:41], v[44:45]
	v_pk_mul_f32 v[44:45], v[32:33], v[50:51] op_sel_hi:[1,0]
	v_cvt_pk_bf16_f32 v40, v40, v41
	v_pk_mul_f32 v[42:43], v[48:49], v[42:43] op_sel_hi:[0,1]
	v_exp_f32_e32 v44, v44
	v_exp_f32_e32 v45, v45
	v_pk_mul_f32 v[42:43], v[46:47], v[42:43]
	v_pk_mul_f32 v[32:33], v[32:33], v[36:37]
	v_cvt_pk_bf16_f32 v41, v42, v43
	v_pk_add_f32 v[42:43], v[44:45], 1.0 op_sel_hi:[1,0]
	v_pk_mul_f32 v[44:45], v[34:35], v[50:51] op_sel_hi:[1,0]
	v_rcp_f32_e32 v42, v42
	v_exp_f32_e32 v44, v44
	v_exp_f32_e32 v45, v45
	v_rcp_f32_e32 v43, v43
	v_pk_mul_f32 v[34:35], v[34:35], v[38:39]
	v_pk_add_f32 v[36:37], v[44:45], 1.0 op_sel_hi:[1,0]
	s_nop 0
	v_rcp_f32_e32 v36, v36
	v_rcp_f32_e32 v37, v37
	v_pk_mul_f32 v[38:39], v[48:49], v[42:43] op_sel_hi:[0,1]
	v_pk_mul_f32 v[32:33], v[32:33], v[38:39]
	s_nop 0
	v_cvt_pk_bf16_f32 v42, v32, v33
	v_pk_mul_f32 v[32:33], v[48:49], v[36:37] op_sel_hi:[0,1]
	v_pk_mul_f32 v[32:33], v[34:35], v[32:33]
	s_nop 0
	v_cvt_pk_bf16_f32 v43, v32, v33
	s_waitcnt lgkmcnt(0)
	v_fmamk_f32 v33, v138, 0x3a800000, v155
	v_rsq_f32_e32 v35, v33
	v_add_u32_e32 v32, 0x90, v156
	v_ashrrev_i32_e32 v32, 4, v32
	v_mad_i64_i32 v[32:33], s[0:1], v32, s75, v[136:137]
	v_mul_f32_e32 v34, 0xbfb8aa3b, v35
	v_pk_mul_f32 v[36:37], v[24:25], v[34:35] op_sel_hi:[1,0]
	v_pk_mul_f32 v[26:27], v[26:27], v[34:35] op_sel_hi:[1,0]
	v_exp_f32_e32 v36, v36
	v_exp_f32_e32 v37, v37
	v_exp_f32_e32 v26, v26
	v_exp_f32_e32 v27, v27
	v_lshlrev_b64 v[32:33], 10, v[32:33]
	v_pk_add_f32 v[36:37], v[36:37], 1.0 op_sel_hi:[1,0]
	v_lshl_add_u64 v[32:33], s[24:25], 0, v[32:33]
	v_rcp_f32_e32 v36, v36
	v_rcp_f32_e32 v37, v37
	v_lshl_add_u64 v[32:33], v[32:33], 0, v[128:129]
	global_store_dwordx4 v[32:33], v[40:43], off nt
	v_mul_f32_e32 v32, v35, v35
	v_pk_add_f32 v[26:27], v[26:27], 1.0 op_sel_hi:[1,0]
	v_pk_mul_f32 v[24:25], v[24:25], v[28:29]
	v_pk_mul_f32 v[28:29], v[32:33], v[36:37] op_sel_hi:[0,1]
	v_rcp_f32_e32 v26, v26
	v_rcp_f32_e32 v27, v27
	v_pk_mul_f32 v[24:25], v[24:25], v[28:29]
	v_pk_mul_f32 v[28:29], v[16:17], v[34:35] op_sel_hi:[1,0]
	v_cvt_pk_bf16_f32 v24, v24, v25
	v_pk_mul_f32 v[26:27], v[32:33], v[26:27] op_sel_hi:[0,1]
	v_exp_f32_e32 v28, v28
	v_exp_f32_e32 v29, v29
	v_pk_mul_f32 v[26:27], v[30:31], v[26:27]
	v_pk_mul_f32 v[16:17], v[16:17], v[20:21]
	v_cvt_pk_bf16_f32 v25, v26, v27
	v_pk_add_f32 v[26:27], v[28:29], 1.0 op_sel_hi:[1,0]
	v_pk_mul_f32 v[28:29], v[18:19], v[34:35] op_sel_hi:[1,0]
	v_rcp_f32_e32 v26, v26
	v_exp_f32_e32 v28, v28
	v_exp_f32_e32 v29, v29
	v_rcp_f32_e32 v27, v27
	v_pk_mul_f32 v[18:19], v[18:19], v[22:23]
	v_pk_add_f32 v[20:21], v[28:29], 1.0 op_sel_hi:[1,0]
	s_nop 0
	v_rcp_f32_e32 v20, v20
	v_rcp_f32_e32 v21, v21
	v_pk_mul_f32 v[22:23], v[32:33], v[26:27] op_sel_hi:[0,1]
	v_pk_mul_f32 v[16:17], v[16:17], v[22:23]
	s_nop 0
	v_cvt_pk_bf16_f32 v26, v16, v17
	v_pk_mul_f32 v[16:17], v[32:33], v[20:21] op_sel_hi:[0,1]
	v_pk_mul_f32 v[16:17], v[18:19], v[16:17]
	s_nop 0
	v_cvt_pk_bf16_f32 v27, v16, v17
	v_fmamk_f32 v17, v139, 0x3a800000, v155
	v_rsq_f32_e32 v19, v17
	v_add_u32_e32 v16, 0xa0, v156
	v_ashrrev_i32_e32 v16, 4, v16
	v_mad_i64_i32 v[16:17], s[0:1], v16, s75, v[136:137]
	v_mul_f32_e32 v18, 0xbfb8aa3b, v19
	v_pk_mul_f32 v[20:21], v[8:9], v[18:19] op_sel_hi:[1,0]
	v_pk_mul_f32 v[10:11], v[10:11], v[18:19] op_sel_hi:[1,0]
	v_exp_f32_e32 v20, v20
	v_exp_f32_e32 v21, v21
	v_exp_f32_e32 v10, v10
	v_exp_f32_e32 v11, v11
	v_lshlrev_b64 v[16:17], 10, v[16:17]
	v_pk_add_f32 v[20:21], v[20:21], 1.0 op_sel_hi:[1,0]
	v_lshl_add_u64 v[16:17], s[24:25], 0, v[16:17]
	v_rcp_f32_e32 v20, v20
	v_rcp_f32_e32 v21, v21
	v_lshl_add_u64 v[16:17], v[16:17], 0, v[128:129]
	global_store_dwordx4 v[16:17], v[24:27], off nt
	v_mul_f32_e32 v16, v19, v19
	v_pk_add_f32 v[10:11], v[10:11], 1.0 op_sel_hi:[1,0]
	v_pk_mul_f32 v[8:9], v[8:9], v[12:13]
	v_pk_mul_f32 v[12:13], v[16:17], v[20:21] op_sel_hi:[0,1]
	v_rcp_f32_e32 v10, v10
	v_rcp_f32_e32 v11, v11
	v_pk_mul_f32 v[8:9], v[8:9], v[12:13]
	v_pk_mul_f32 v[12:13], v[0:1], v[18:19] op_sel_hi:[1,0]
	v_cvt_pk_bf16_f32 v8, v8, v9
	v_pk_mul_f32 v[10:11], v[16:17], v[10:11] op_sel_hi:[0,1]
	v_exp_f32_e32 v12, v12
	v_exp_f32_e32 v13, v13
	v_pk_mul_f32 v[10:11], v[14:15], v[10:11]
	v_pk_mul_f32 v[0:1], v[0:1], v[4:5]
	v_cvt_pk_bf16_f32 v9, v10, v11
	v_pk_add_f32 v[10:11], v[12:13], 1.0 op_sel_hi:[1,0]
	v_pk_mul_f32 v[12:13], v[2:3], v[18:19] op_sel_hi:[1,0]
	v_rcp_f32_e32 v10, v10
	v_exp_f32_e32 v12, v12
	v_exp_f32_e32 v13, v13
	v_rcp_f32_e32 v11, v11
	v_pk_mul_f32 v[2:3], v[2:3], v[6:7]
	v_pk_add_f32 v[4:5], v[12:13], 1.0 op_sel_hi:[1,0]
	s_nop 0
	v_rcp_f32_e32 v4, v4
	v_rcp_f32_e32 v5, v5
	v_pk_mul_f32 v[6:7], v[16:17], v[10:11] op_sel_hi:[0,1]
	v_pk_mul_f32 v[0:1], v[0:1], v[6:7]
	s_nop 0
	v_cvt_pk_bf16_f32 v10, v0, v1
	v_pk_mul_f32 v[0:1], v[16:17], v[4:5] op_sel_hi:[0,1]
	v_pk_mul_f32 v[0:1], v[2:3], v[0:1]
	s_nop 0
	v_cvt_pk_bf16_f32 v11, v0, v1
	v_add_u32_e32 v0, 0xb0, v156
	v_ashrrev_i32_e32 v0, 4, v0
	v_mad_i64_i32 v[0:1], s[0:1], v0, s75, v[136:137]
	v_lshlrev_b64 v[0:1], 10, v[0:1]
	v_lshl_add_u64 v[0:1], s[24:25], 0, v[0:1]
	v_lshl_add_u64 v[0:1], v[0:1], 0, v[128:129]
	global_store_dwordx4 v[0:1], v[8:11], off nt
	s_cmp_eq_u64 s[14:15], 0
	s_cbranch_scc1 .Lee_p4
	s_barrier
.Lee_p4:
	s_cbranch_vccnz .LBB0_481
	s_andn2_b64 vcc, exec, s[6:7]
	s_cbranch_vccnz .LBB0_480
	s_barrier
	s_branch .LBB0_480
